# attention tile loops: 16-value row-max tree as 8 v_max3/v_max ops (was 20 with canonicalizing v_max x,x) at all six sites
# speedup vs baseline: 1.0081x; 1.0018x over previous
.LBB0_161:
	s_ashr_i32 s42, s86, 3
	s_lshl_b32 s43, 1, s42
	v_and_b32_e32 v0, s43, v193
	s_cmp_ge_i32 s42, s2
	v_cmp_ne_u32_e32 vcc, 0, v0
	s_cselect_b64 s[42:43], -1, 0
	s_or_b64 vcc, s[42:43], vcc
	s_nop 3
	v_cndmask_b32_e32 v11, v226, v80, vcc
	v_cndmask_b32_e32 v15, v226, v82, vcc
	v_cndmask_b32_e32 v80, v226, v83, vcc
	v_cndmask_b32_e32 v10, v226, v86, vcc
	v_cndmask_b32_e32 v9, v226, v87, vcc
	v_cndmask_b32_e32 v14, v226, v81, vcc
	v_cndmask_b32_e32 v8, v226, v88, vcc
	v_cndmask_b32_e32 v7, v226, v89, vcc
	v_cndmask_b32_e32 v6, v226, v90, vcc
	v_cndmask_b32_e32 v5, v226, v91, vcc
	v_cndmask_b32_e32 v13, v226, v84, vcc
	v_cndmask_b32_e32 v2, v226, v94, vcc
	v_cndmask_b32_e32 v0, v226, v95, vcc
	v_cndmask_b32_e32 v12, v226, v85, vcc
	v_cndmask_b32_e32 v4, v226, v92, vcc
	v_cndmask_b32_e32 v3, v226, v93, vcc
	v_max3_f32 v81, v80, v15, v9
	v_max3_f32 v82, v10, v7, v8
	v_max3_f32 v83, v5, v6, v0
	v_max3_f32 v84, v2, v4, v3
	v_max3_f32 v85, v11, v14, v13
	v_max3_f32 v81, v81, v82, v12
	v_max3_f32 v83, v83, v84, v85
	v_max_f32_e32 v81, v81, v83
	v_add_f32_e32 v82, 0x41000000, v203
	v_cmp_gt_f32_e32 vcc, v81, v82
	s_cbranch_vccz .LBB0_163
	v_and_b32_e32 v83, 64, v225
	v_xor_b32_e32 v82, 32, v225
	v_add_u32_e32 v83, 64, v83
	v_cmp_lt_i32_e32 vcc, v82, v83
	s_nop 1
	v_cndmask_b32_e32 v82, v225, v82, vcc
	v_lshlrev_b32_e32 v82, 2, v82
	ds_bpermute_b32 v82, v82, v81
	s_waitcnt lgkmcnt(0)
	v_max3_f32 v81, v203, v81, v82
	v_sub_f32_e32 v82, v203, v81
	v_exp_f32_e32 v82, v82
	v_mov_b32_e32 v203, v81
	v_pk_mul_f32 v[78:79], v[78:79], v[82:83] op_sel_hi:[1,0]
	v_pk_mul_f32 v[76:77], v[76:77], v[82:83] op_sel_hi:[1,0]
	v_pk_mul_f32 v[74:75], v[74:75], v[82:83] op_sel_hi:[1,0]
	v_pk_mul_f32 v[72:73], v[72:73], v[82:83] op_sel_hi:[1,0]
	v_pk_mul_f32 v[70:71], v[70:71], v[82:83] op_sel_hi:[1,0]
	v_pk_mul_f32 v[68:69], v[68:69], v[82:83] op_sel_hi:[1,0]
	v_pk_mul_f32 v[66:67], v[66:67], v[82:83] op_sel_hi:[1,0]
	v_pk_mul_f32 v[64:65], v[64:65], v[82:83] op_sel_hi:[1,0]
	v_pk_mul_f32 v[62:63], v[62:63], v[82:83] op_sel_hi:[1,0]
	v_pk_mul_f32 v[60:61], v[60:61], v[82:83] op_sel_hi:[1,0]
	v_pk_mul_f32 v[58:59], v[58:59], v[82:83] op_sel_hi:[1,0]
	v_pk_mul_f32 v[56:57], v[56:57], v[82:83] op_sel_hi:[1,0]
	v_pk_mul_f32 v[54:55], v[54:55], v[82:83] op_sel_hi:[1,0]
	v_pk_mul_f32 v[52:53], v[52:53], v[82:83] op_sel_hi:[1,0]
	v_pk_mul_f32 v[50:51], v[50:51], v[82:83] op_sel_hi:[1,0]
	v_pk_mul_f32 v[48:49], v[48:49], v[82:83] op_sel_hi:[1,0]
	v_pk_mul_f32 v[46:47], v[46:47], v[82:83] op_sel_hi:[1,0]
	v_pk_mul_f32 v[44:45], v[44:45], v[82:83] op_sel_hi:[1,0]
	v_pk_mul_f32 v[42:43], v[42:43], v[82:83] op_sel_hi:[1,0]
	v_pk_mul_f32 v[40:41], v[40:41], v[82:83] op_sel_hi:[1,0]
	v_pk_mul_f32 v[38:39], v[38:39], v[82:83] op_sel_hi:[1,0]
	v_pk_mul_f32 v[36:37], v[36:37], v[82:83] op_sel_hi:[1,0]
	v_pk_mul_f32 v[34:35], v[34:35], v[82:83] op_sel_hi:[1,0]
	v_pk_mul_f32 v[32:33], v[32:33], v[82:83] op_sel_hi:[1,0]
	v_pk_mul_f32 v[30:31], v[30:31], v[82:83] op_sel_hi:[1,0]
	v_pk_mul_f32 v[28:29], v[28:29], v[82:83] op_sel_hi:[1,0]
	v_pk_mul_f32 v[26:27], v[26:27], v[82:83] op_sel_hi:[1,0]
	v_pk_mul_f32 v[24:25], v[24:25], v[82:83] op_sel_hi:[1,0]
	v_pk_mul_f32 v[22:23], v[22:23], v[82:83] op_sel_hi:[1,0]
	v_pk_mul_f32 v[20:21], v[20:21], v[82:83] op_sel_hi:[1,0]
	v_pk_mul_f32 v[18:19], v[18:19], v[82:83] op_sel_hi:[1,0]
	v_pk_mul_f32 v[16:17], v[16:17], v[82:83] op_sel_hi:[1,0]
	v_mul_f32_e32 v205, v205, v82

.LBB0_165:
	s_cmp_le_i32 s87, s92
	s_cselect_b64 s[42:43], -1, 0
	s_ashr_i32 s60, s87, 3
	s_cmp_ge_i32 s60, s2
	s_cselect_b64 s[54:55], -1, 0
	s_lshl_b32 s60, 1, s60
	v_add_f32_e32 v0, v2, v0
	v_and_b32_e32 v2, s60, v193
	v_cmp_ne_u32_e32 vcc, 0, v2
	s_or_b64 s[54:55], s[54:55], vcc
	v_add_f32_e32 v11, v11, v14
	v_add_f32_e32 v14, v15, v210
	v_add_f32_e32 v12, v13, v12
	v_add_f32_e32 v9, v10, v9
	s_and_b64 vcc, s[42:43], s[54:55]
	v_add_f32_e32 v11, v11, v14
	v_add_f32_e32 v9, v12, v9
	v_add_f32_e32 v7, v8, v7
	v_add_f32_e32 v5, v6, v5
	v_cndmask_b32_e32 v15, v226, v82, vcc
	v_cndmask_b32_e32 v14, v226, v83, vcc
	v_add_f32_e32 v9, v11, v9
	v_add_f32_e32 v5, v7, v5
	v_cndmask_b32_e32 v13, v226, v84, vcc
	v_cndmask_b32_e32 v11, v226, v86, vcc
	v_cndmask_b32_e32 v10, v226, v87, vcc
	v_cndmask_b32_e32 v84, v226, v80, vcc
	v_cndmask_b32_e32 v80, v226, v81, vcc
	v_add_f32_e32 v5, v5, v9
	v_cndmask_b32_e32 v9, v226, v88, vcc
	v_cndmask_b32_e32 v8, v226, v89, vcc
	v_add_f32_e32 v3, v4, v3
	v_cndmask_b32_e32 v7, v226, v90, vcc
	v_cndmask_b32_e32 v6, v226, v91, vcc
	v_cndmask_b32_e32 v12, v226, v85, vcc
	v_add_f32_e32 v0, v3, v0
	v_cndmask_b32_e32 v3, v226, v94, vcc
	v_cndmask_b32_e32 v2, v226, v95, vcc
	v_add_f32_e32 v0, v0, v5
	v_cndmask_b32_e32 v5, v226, v92, vcc
	v_cndmask_b32_e32 v4, v226, v93, vcc
	v_max3_f32 v81, v14, v15, v10
	v_max3_f32 v82, v11, v8, v9
	v_max3_f32 v83, v6, v7, v2
	v_max3_f32 v85, v3, v5, v4
	v_max3_f32 v86, v84, v80, v13
	v_max3_f32 v81, v81, v82, v12
	v_max3_f32 v83, v83, v85, v86
	v_max_f32_e32 v81, v81, v83
	v_add_f32_e32 v82, 0x41000000, v203
	v_add_f32_e32 v0, v205, v0
	v_cmp_gt_f32_e32 vcc, v81, v82
	s_cbranch_vccz .LBB0_158
	v_and_b32_e32 v83, 64, v225
	v_xor_b32_e32 v82, 32, v225
	v_add_u32_e32 v83, 64, v83
	v_cmp_lt_i32_e32 vcc, v82, v83
	s_nop 1
	v_cndmask_b32_e32 v82, v225, v82, vcc
	v_lshlrev_b32_e32 v82, 2, v82
	ds_bpermute_b32 v82, v82, v81
	s_waitcnt lgkmcnt(0)
	v_max3_f32 v81, v203, v81, v82
	v_sub_f32_e32 v82, v203, v81
	v_exp_f32_e32 v82, v82
	v_mov_b32_e32 v203, v81
	v_pk_mul_f32 v[78:79], v[78:79], v[82:83] op_sel_hi:[1,0]
	v_pk_mul_f32 v[76:77], v[76:77], v[82:83] op_sel_hi:[1,0]
	v_pk_mul_f32 v[74:75], v[74:75], v[82:83] op_sel_hi:[1,0]
	v_pk_mul_f32 v[72:73], v[72:73], v[82:83] op_sel_hi:[1,0]
	v_pk_mul_f32 v[70:71], v[70:71], v[82:83] op_sel_hi:[1,0]
	v_pk_mul_f32 v[68:69], v[68:69], v[82:83] op_sel_hi:[1,0]
	v_pk_mul_f32 v[66:67], v[66:67], v[82:83] op_sel_hi:[1,0]
	v_pk_mul_f32 v[64:65], v[64:65], v[82:83] op_sel_hi:[1,0]
	v_pk_mul_f32 v[62:63], v[62:63], v[82:83] op_sel_hi:[1,0]
	v_pk_mul_f32 v[60:61], v[60:61], v[82:83] op_sel_hi:[1,0]
	v_pk_mul_f32 v[58:59], v[58:59], v[82:83] op_sel_hi:[1,0]
	v_pk_mul_f32 v[56:57], v[56:57], v[82:83] op_sel_hi:[1,0]
	v_pk_mul_f32 v[54:55], v[54:55], v[82:83] op_sel_hi:[1,0]
	v_pk_mul_f32 v[52:53], v[52:53], v[82:83] op_sel_hi:[1,0]
	v_pk_mul_f32 v[50:51], v[50:51], v[82:83] op_sel_hi:[1,0]
	v_pk_mul_f32 v[48:49], v[48:49], v[82:83] op_sel_hi:[1,0]
	v_pk_mul_f32 v[46:47], v[46:47], v[82:83] op_sel_hi:[1,0]
	v_pk_mul_f32 v[44:45], v[44:45], v[82:83] op_sel_hi:[1,0]
	v_pk_mul_f32 v[42:43], v[42:43], v[82:83] op_sel_hi:[1,0]
	v_pk_mul_f32 v[40:41], v[40:41], v[82:83] op_sel_hi:[1,0]
	v_pk_mul_f32 v[38:39], v[38:39], v[82:83] op_sel_hi:[1,0]
	v_pk_mul_f32 v[36:37], v[36:37], v[82:83] op_sel_hi:[1,0]
	v_pk_mul_f32 v[34:35], v[34:35], v[82:83] op_sel_hi:[1,0]
	v_pk_mul_f32 v[32:33], v[32:33], v[82:83] op_sel_hi:[1,0]
	v_pk_mul_f32 v[30:31], v[30:31], v[82:83] op_sel_hi:[1,0]
	v_pk_mul_f32 v[28:29], v[28:29], v[82:83] op_sel_hi:[1,0]
	v_pk_mul_f32 v[26:27], v[26:27], v[82:83] op_sel_hi:[1,0]
	v_pk_mul_f32 v[24:25], v[24:25], v[82:83] op_sel_hi:[1,0]
	v_pk_mul_f32 v[22:23], v[22:23], v[82:83] op_sel_hi:[1,0]
	v_pk_mul_f32 v[20:21], v[20:21], v[82:83] op_sel_hi:[1,0]
	v_pk_mul_f32 v[18:19], v[18:19], v[82:83] op_sel_hi:[1,0]
	v_pk_mul_f32 v[16:17], v[16:17], v[82:83] op_sel_hi:[1,0]
	v_mul_f32_e32 v0, v0, v82
	s_branch .LBB0_158

.LBB0_175:
	s_nop 10
	v_max3_f32 v0, v83, v82, v87
	v_max3_f32 v2, v86, v89, v88
	v_max3_f32 v3, v91, v90, v95
	v_max3_f32 v4, v94, v92, v93
	v_max3_f32 v5, v80, v81, v84
	v_max3_f32 v0, v0, v2, v85
	v_max3_f32 v3, v3, v4, v5
	v_max_f32_e32 v0, v0, v3
	v_add_f32_e32 v2, 0x41000000, v232
	v_cmp_gt_f32_e32 vcc, v0, v2
	s_cbranch_vccz .LBB0_177
	ds_bpermute_b32 v2, v201, v0
	s_waitcnt lgkmcnt(0)
	v_max3_f32 v2, v232, v0, v2
	v_sub_f32_e32 v0, v232, v2
	v_exp_f32_e32 v0, v0
	v_mov_b32_e32 v232, v2
	v_pk_mul_f32 v[78:79], v[78:79], v[0:1] op_sel_hi:[1,0]
	v_pk_mul_f32 v[76:77], v[76:77], v[0:1] op_sel_hi:[1,0]
	v_pk_mul_f32 v[74:75], v[74:75], v[0:1] op_sel_hi:[1,0]
	v_pk_mul_f32 v[72:73], v[72:73], v[0:1] op_sel_hi:[1,0]
	v_pk_mul_f32 v[70:71], v[70:71], v[0:1] op_sel_hi:[1,0]
	v_pk_mul_f32 v[68:69], v[68:69], v[0:1] op_sel_hi:[1,0]
	v_pk_mul_f32 v[66:67], v[66:67], v[0:1] op_sel_hi:[1,0]
	v_pk_mul_f32 v[64:65], v[64:65], v[0:1] op_sel_hi:[1,0]
	v_pk_mul_f32 v[62:63], v[62:63], v[0:1] op_sel_hi:[1,0]
	v_pk_mul_f32 v[60:61], v[60:61], v[0:1] op_sel_hi:[1,0]
	v_pk_mul_f32 v[58:59], v[58:59], v[0:1] op_sel_hi:[1,0]
	v_pk_mul_f32 v[56:57], v[56:57], v[0:1] op_sel_hi:[1,0]
	v_pk_mul_f32 v[54:55], v[54:55], v[0:1] op_sel_hi:[1,0]
	v_pk_mul_f32 v[52:53], v[52:53], v[0:1] op_sel_hi:[1,0]
	v_pk_mul_f32 v[50:51], v[50:51], v[0:1] op_sel_hi:[1,0]
	v_pk_mul_f32 v[48:49], v[48:49], v[0:1] op_sel_hi:[1,0]
	v_pk_mul_f32 v[46:47], v[46:47], v[0:1] op_sel_hi:[1,0]
	v_pk_mul_f32 v[44:45], v[44:45], v[0:1] op_sel_hi:[1,0]
	v_pk_mul_f32 v[42:43], v[42:43], v[0:1] op_sel_hi:[1,0]
	v_pk_mul_f32 v[40:41], v[40:41], v[0:1] op_sel_hi:[1,0]
	v_pk_mul_f32 v[38:39], v[38:39], v[0:1] op_sel_hi:[1,0]
	v_pk_mul_f32 v[36:37], v[36:37], v[0:1] op_sel_hi:[1,0]
	v_pk_mul_f32 v[34:35], v[34:35], v[0:1] op_sel_hi:[1,0]
	v_pk_mul_f32 v[32:33], v[32:33], v[0:1] op_sel_hi:[1,0]
	v_pk_mul_f32 v[30:31], v[30:31], v[0:1] op_sel_hi:[1,0]
	v_pk_mul_f32 v[28:29], v[28:29], v[0:1] op_sel_hi:[1,0]
	v_pk_mul_f32 v[26:27], v[26:27], v[0:1] op_sel_hi:[1,0]
	v_pk_mul_f32 v[24:25], v[24:25], v[0:1] op_sel_hi:[1,0]
	v_pk_mul_f32 v[22:23], v[22:23], v[0:1] op_sel_hi:[1,0]
	v_pk_mul_f32 v[20:21], v[20:21], v[0:1] op_sel_hi:[1,0]
	v_pk_mul_f32 v[18:19], v[18:19], v[0:1] op_sel_hi:[1,0]
	v_pk_mul_f32 v[16:17], v[16:17], v[0:1] op_sel_hi:[1,0]
	v_mul_f32_e32 v233, v233, v0

.LBB0_179:
	v_add_f32_e32 v0, v0, v2
	v_add_f32_e32 v2, v3, v4
	v_add_f32_e32 v0, v0, v2
	v_add_f32_e32 v2, v5, v6
	v_add_f32_e32 v3, v7, v9
	v_add_f32_e32 v2, v2, v3
	v_add_f32_e32 v0, v0, v2
	v_add_f32_e32 v2, v8, v10
	v_add_f32_e32 v3, v11, v13
	s_cmp_gt_u32 s57, s92
	v_add_f32_e32 v2, v2, v3
	s_cselect_b64 s[42:43], -1, 0
	v_add_f32_e32 v0, v2, v0
	v_add_f32_e32 v2, v12, v14
	v_add_f32_e32 v3, v15, v234
	v_cndmask_b32_e64 v15, v82, v226, s[42:43]
	v_cndmask_b32_e64 v14, v83, v226, s[42:43]
	v_cndmask_b32_e64 v13, v84, v226, s[42:43]
	v_cndmask_b32_e64 v11, v86, v226, s[42:43]
	v_cndmask_b32_e64 v10, v87, v226, s[42:43]
	v_cndmask_b32_e64 v84, v80, v226, s[42:43]
	v_cndmask_b32_e64 v80, v81, v226, s[42:43]
	v_cndmask_b32_e64 v9, v88, v226, s[42:43]
	v_cndmask_b32_e64 v8, v89, v226, s[42:43]
	v_add_f32_e32 v2, v2, v3
	v_cndmask_b32_e64 v7, v90, v226, s[42:43]
	v_cndmask_b32_e64 v6, v91, v226, s[42:43]
	v_cndmask_b32_e64 v12, v85, v226, s[42:43]
	v_add_f32_e32 v0, v2, v0
	v_cndmask_b32_e64 v3, v94, v226, s[42:43]
	v_cndmask_b32_e64 v2, v95, v226, s[42:43]
	v_cndmask_b32_e64 v5, v92, v226, s[42:43]
	v_cndmask_b32_e64 v4, v93, v226, s[42:43]
	v_max3_f32 v81, v14, v15, v10
	v_max3_f32 v82, v11, v8, v9
	v_max3_f32 v83, v6, v7, v2
	v_max3_f32 v85, v3, v5, v4
	v_max3_f32 v86, v84, v80, v13
	v_max3_f32 v81, v81, v82, v12
	v_max3_f32 v83, v83, v85, v86
	v_max_f32_e32 v81, v81, v83
	v_add_f32_e32 v82, 0x41000000, v232
	v_add_f32_e32 v0, v233, v0
	v_cmp_gt_f32_e32 vcc, v81, v82
	s_cbranch_vccz .LBB0_172
	ds_bpermute_b32 v82, v201, v81
	s_waitcnt lgkmcnt(0)
	v_max3_f32 v81, v232, v81, v82
	v_sub_f32_e32 v82, v232, v81
	v_exp_f32_e32 v82, v82
	v_mov_b32_e32 v232, v81
	v_pk_mul_f32 v[78:79], v[78:79], v[82:83] op_sel_hi:[1,0]
	v_pk_mul_f32 v[76:77], v[76:77], v[82:83] op_sel_hi:[1,0]
	v_pk_mul_f32 v[74:75], v[74:75], v[82:83] op_sel_hi:[1,0]
	v_pk_mul_f32 v[72:73], v[72:73], v[82:83] op_sel_hi:[1,0]
	v_pk_mul_f32 v[70:71], v[70:71], v[82:83] op_sel_hi:[1,0]
	v_pk_mul_f32 v[68:69], v[68:69], v[82:83] op_sel_hi:[1,0]
	v_pk_mul_f32 v[66:67], v[66:67], v[82:83] op_sel_hi:[1,0]
	v_pk_mul_f32 v[64:65], v[64:65], v[82:83] op_sel_hi:[1,0]
	v_pk_mul_f32 v[62:63], v[62:63], v[82:83] op_sel_hi:[1,0]
	v_pk_mul_f32 v[60:61], v[60:61], v[82:83] op_sel_hi:[1,0]
	v_pk_mul_f32 v[58:59], v[58:59], v[82:83] op_sel_hi:[1,0]
	v_pk_mul_f32 v[56:57], v[56:57], v[82:83] op_sel_hi:[1,0]
	v_pk_mul_f32 v[54:55], v[54:55], v[82:83] op_sel_hi:[1,0]
	v_pk_mul_f32 v[52:53], v[52:53], v[82:83] op_sel_hi:[1,0]
	v_pk_mul_f32 v[50:51], v[50:51], v[82:83] op_sel_hi:[1,0]
	v_pk_mul_f32 v[48:49], v[48:49], v[82:83] op_sel_hi:[1,0]
	v_pk_mul_f32 v[46:47], v[46:47], v[82:83] op_sel_hi:[1,0]
	v_pk_mul_f32 v[44:45], v[44:45], v[82:83] op_sel_hi:[1,0]
	v_pk_mul_f32 v[42:43], v[42:43], v[82:83] op_sel_hi:[1,0]
	v_pk_mul_f32 v[40:41], v[40:41], v[82:83] op_sel_hi:[1,0]
	v_pk_mul_f32 v[38:39], v[38:39], v[82:83] op_sel_hi:[1,0]
	v_pk_mul_f32 v[36:37], v[36:37], v[82:83] op_sel_hi:[1,0]
	v_pk_mul_f32 v[34:35], v[34:35], v[82:83] op_sel_hi:[1,0]
	v_pk_mul_f32 v[32:33], v[32:33], v[82:83] op_sel_hi:[1,0]
	v_pk_mul_f32 v[30:31], v[30:31], v[82:83] op_sel_hi:[1,0]
	v_pk_mul_f32 v[28:29], v[28:29], v[82:83] op_sel_hi:[1,0]
	v_pk_mul_f32 v[26:27], v[26:27], v[82:83] op_sel_hi:[1,0]
	v_pk_mul_f32 v[24:25], v[24:25], v[82:83] op_sel_hi:[1,0]
	v_pk_mul_f32 v[22:23], v[22:23], v[82:83] op_sel_hi:[1,0]
	v_pk_mul_f32 v[20:21], v[20:21], v[82:83] op_sel_hi:[1,0]
	v_pk_mul_f32 v[18:19], v[18:19], v[82:83] op_sel_hi:[1,0]
	v_pk_mul_f32 v[16:17], v[16:17], v[82:83] op_sel_hi:[1,0]
	v_mul_f32_e32 v0, v0, v82
	s_branch .LBB0_172

.LBB0_185:
	s_nop 10
	v_max3_f32 v0, v83, v82, v87
	v_max3_f32 v2, v86, v89, v88
	v_max3_f32 v3, v91, v90, v95
	v_max3_f32 v4, v94, v92, v93
	v_max3_f32 v5, v80, v81, v84
	v_max3_f32 v0, v0, v2, v85
	v_max3_f32 v3, v3, v4, v5
	v_max_f32_e32 v0, v0, v3
	v_add_f32_e32 v2, 0x41000000, v210
	v_cmp_gt_f32_e32 vcc, v0, v2
	s_cbranch_vccz .LBB0_187
	ds_bpermute_b32 v2, v201, v0
	s_waitcnt lgkmcnt(0)
	v_max3_f32 v2, v210, v0, v2
	v_sub_f32_e32 v0, v210, v2
	v_exp_f32_e32 v0, v0
	v_mov_b32_e32 v210, v2
	v_pk_mul_f32 v[78:79], v[78:79], v[0:1] op_sel_hi:[1,0]
	v_pk_mul_f32 v[76:77], v[76:77], v[0:1] op_sel_hi:[1,0]
	v_pk_mul_f32 v[74:75], v[74:75], v[0:1] op_sel_hi:[1,0]
	v_pk_mul_f32 v[72:73], v[72:73], v[0:1] op_sel_hi:[1,0]
	v_pk_mul_f32 v[70:71], v[70:71], v[0:1] op_sel_hi:[1,0]
	v_pk_mul_f32 v[68:69], v[68:69], v[0:1] op_sel_hi:[1,0]
	v_pk_mul_f32 v[66:67], v[66:67], v[0:1] op_sel_hi:[1,0]
	v_pk_mul_f32 v[64:65], v[64:65], v[0:1] op_sel_hi:[1,0]
	v_pk_mul_f32 v[62:63], v[62:63], v[0:1] op_sel_hi:[1,0]
	v_pk_mul_f32 v[60:61], v[60:61], v[0:1] op_sel_hi:[1,0]
	v_pk_mul_f32 v[58:59], v[58:59], v[0:1] op_sel_hi:[1,0]
	v_pk_mul_f32 v[56:57], v[56:57], v[0:1] op_sel_hi:[1,0]
	v_pk_mul_f32 v[54:55], v[54:55], v[0:1] op_sel_hi:[1,0]
	v_pk_mul_f32 v[52:53], v[52:53], v[0:1] op_sel_hi:[1,0]
	v_pk_mul_f32 v[50:51], v[50:51], v[0:1] op_sel_hi:[1,0]
	v_pk_mul_f32 v[48:49], v[48:49], v[0:1] op_sel_hi:[1,0]
	v_pk_mul_f32 v[46:47], v[46:47], v[0:1] op_sel_hi:[1,0]
	v_pk_mul_f32 v[44:45], v[44:45], v[0:1] op_sel_hi:[1,0]
	v_pk_mul_f32 v[42:43], v[42:43], v[0:1] op_sel_hi:[1,0]
	v_pk_mul_f32 v[40:41], v[40:41], v[0:1] op_sel_hi:[1,0]
	v_pk_mul_f32 v[38:39], v[38:39], v[0:1] op_sel_hi:[1,0]
	v_pk_mul_f32 v[36:37], v[36:37], v[0:1] op_sel_hi:[1,0]
	v_pk_mul_f32 v[34:35], v[34:35], v[0:1] op_sel_hi:[1,0]
	v_pk_mul_f32 v[32:33], v[32:33], v[0:1] op_sel_hi:[1,0]
	v_pk_mul_f32 v[30:31], v[30:31], v[0:1] op_sel_hi:[1,0]
	v_pk_mul_f32 v[28:29], v[28:29], v[0:1] op_sel_hi:[1,0]
	v_pk_mul_f32 v[26:27], v[26:27], v[0:1] op_sel_hi:[1,0]
	v_pk_mul_f32 v[24:25], v[24:25], v[0:1] op_sel_hi:[1,0]
	v_pk_mul_f32 v[22:23], v[22:23], v[0:1] op_sel_hi:[1,0]
	v_pk_mul_f32 v[20:21], v[20:21], v[0:1] op_sel_hi:[1,0]
	v_pk_mul_f32 v[18:19], v[18:19], v[0:1] op_sel_hi:[1,0]
	v_pk_mul_f32 v[16:17], v[16:17], v[0:1] op_sel_hi:[1,0]
	v_mul_f32_e32 v211, v211, v0

.LBB0_189:
	v_add_f32_e32 v0, v0, v2
	v_add_f32_e32 v2, v3, v4
	v_add_f32_e32 v0, v0, v2
	v_add_f32_e32 v2, v5, v6
	v_add_f32_e32 v3, v7, v9
	v_add_f32_e32 v2, v2, v3
	v_add_f32_e32 v0, v0, v2
	v_add_f32_e32 v2, v8, v10
	v_add_f32_e32 v3, v11, v13
	s_cmp_gt_u32 s2, s92
	v_add_f32_e32 v2, v2, v3
	s_cselect_b64 s[42:43], -1, 0
	v_add_f32_e32 v0, v2, v0
	v_add_f32_e32 v2, v12, v14
	v_add_f32_e32 v3, v15, v212
	v_cndmask_b32_e64 v15, v82, v226, s[42:43]
	v_cndmask_b32_e64 v14, v83, v226, s[42:43]
	v_cndmask_b32_e64 v13, v84, v226, s[42:43]
	v_cndmask_b32_e64 v11, v86, v226, s[42:43]
	v_cndmask_b32_e64 v10, v87, v226, s[42:43]
	v_cndmask_b32_e64 v84, v80, v226, s[42:43]
	v_cndmask_b32_e64 v80, v81, v226, s[42:43]
	v_cndmask_b32_e64 v9, v88, v226, s[42:43]
	v_cndmask_b32_e64 v8, v89, v226, s[42:43]
	v_add_f32_e32 v2, v2, v3
	v_cndmask_b32_e64 v7, v90, v226, s[42:43]
	v_cndmask_b32_e64 v6, v91, v226, s[42:43]
	v_cndmask_b32_e64 v12, v85, v226, s[42:43]
	v_add_f32_e32 v0, v2, v0
	v_cndmask_b32_e64 v3, v94, v226, s[42:43]
	v_cndmask_b32_e64 v2, v95, v226, s[42:43]
	v_cndmask_b32_e64 v5, v92, v226, s[42:43]
	v_cndmask_b32_e64 v4, v93, v226, s[42:43]
	v_max3_f32 v81, v14, v15, v10
	v_max3_f32 v82, v11, v8, v9
	v_max3_f32 v83, v6, v7, v2
	v_max3_f32 v85, v3, v5, v4
	v_max3_f32 v86, v84, v80, v13
	v_max3_f32 v81, v81, v82, v12
	v_max3_f32 v83, v83, v85, v86
	v_max_f32_e32 v81, v81, v83
	v_add_f32_e32 v82, 0x41000000, v210
	v_add_f32_e32 v0, v211, v0
	v_cmp_gt_f32_e32 vcc, v81, v82
	s_cbranch_vccz .LBB0_182
	ds_bpermute_b32 v82, v201, v81
	s_waitcnt lgkmcnt(0)
	v_max3_f32 v81, v210, v81, v82
	v_sub_f32_e32 v82, v210, v81
	v_exp_f32_e32 v82, v82
	v_mov_b32_e32 v210, v81
	v_pk_mul_f32 v[78:79], v[78:79], v[82:83] op_sel_hi:[1,0]
	v_pk_mul_f32 v[76:77], v[76:77], v[82:83] op_sel_hi:[1,0]
	v_pk_mul_f32 v[74:75], v[74:75], v[82:83] op_sel_hi:[1,0]
	v_pk_mul_f32 v[72:73], v[72:73], v[82:83] op_sel_hi:[1,0]
	v_pk_mul_f32 v[70:71], v[70:71], v[82:83] op_sel_hi:[1,0]
	v_pk_mul_f32 v[68:69], v[68:69], v[82:83] op_sel_hi:[1,0]
	v_pk_mul_f32 v[66:67], v[66:67], v[82:83] op_sel_hi:[1,0]
	v_pk_mul_f32 v[64:65], v[64:65], v[82:83] op_sel_hi:[1,0]
	v_pk_mul_f32 v[62:63], v[62:63], v[82:83] op_sel_hi:[1,0]
	v_pk_mul_f32 v[60:61], v[60:61], v[82:83] op_sel_hi:[1,0]
	v_pk_mul_f32 v[58:59], v[58:59], v[82:83] op_sel_hi:[1,0]
	v_pk_mul_f32 v[56:57], v[56:57], v[82:83] op_sel_hi:[1,0]
	v_pk_mul_f32 v[54:55], v[54:55], v[82:83] op_sel_hi:[1,0]
	v_pk_mul_f32 v[52:53], v[52:53], v[82:83] op_sel_hi:[1,0]
	v_pk_mul_f32 v[50:51], v[50:51], v[82:83] op_sel_hi:[1,0]
	v_pk_mul_f32 v[48:49], v[48:49], v[82:83] op_sel_hi:[1,0]
	v_pk_mul_f32 v[46:47], v[46:47], v[82:83] op_sel_hi:[1,0]
	v_pk_mul_f32 v[44:45], v[44:45], v[82:83] op_sel_hi:[1,0]
	v_pk_mul_f32 v[42:43], v[42:43], v[82:83] op_sel_hi:[1,0]
	v_pk_mul_f32 v[40:41], v[40:41], v[82:83] op_sel_hi:[1,0]
	v_pk_mul_f32 v[38:39], v[38:39], v[82:83] op_sel_hi:[1,0]
	v_pk_mul_f32 v[36:37], v[36:37], v[82:83] op_sel_hi:[1,0]
	v_pk_mul_f32 v[34:35], v[34:35], v[82:83] op_sel_hi:[1,0]
	v_pk_mul_f32 v[32:33], v[32:33], v[82:83] op_sel_hi:[1,0]
	v_pk_mul_f32 v[30:31], v[30:31], v[82:83] op_sel_hi:[1,0]
	v_pk_mul_f32 v[28:29], v[28:29], v[82:83] op_sel_hi:[1,0]
	v_pk_mul_f32 v[26:27], v[26:27], v[82:83] op_sel_hi:[1,0]
	v_pk_mul_f32 v[24:25], v[24:25], v[82:83] op_sel_hi:[1,0]
	v_pk_mul_f32 v[22:23], v[22:23], v[82:83] op_sel_hi:[1,0]
	v_pk_mul_f32 v[20:21], v[20:21], v[82:83] op_sel_hi:[1,0]
	v_pk_mul_f32 v[18:19], v[18:19], v[82:83] op_sel_hi:[1,0]
	v_pk_mul_f32 v[16:17], v[16:17], v[82:83] op_sel_hi:[1,0]
	v_mul_f32_e32 v0, v0, v82
	s_branch .LBB0_182
